# HGRN: state-independent intra-chunk tiles hoisted ahead of the state chain; both wave halves issue the next chunk loads right after their prep
# speedup vs baseline: 1.0516x; 1.0057x over previous
.LBB0_1016:
	s_waitcnt vmcnt(43)
	v_lshlrev_b32_e32 v41, 16, v47
	v_lshlrev_b32_e32 v40, 16, v52
	v_mov_b32_e32 v146, v41
	v_pk_mul_f32 v[146:147], v[146:147], v[40:41]
	v_rcp_f32_e32 v144, v40
	v_rcp_f32_e32 v145, v146
	v_lshlrev_b32_e32 v35, 16, v75
	v_mul_f32_e32 v35, v40, v35
	v_pk_add_f32 v[40:41], v[40:41], 1.0 op_sel_hi:[1,0] neg_lo:[1,0] neg_hi:[1,0]
	v_cvt_pk_bf16_f32 v35, v35, s0
	v_pk_mul_f32 v[40:41], v[40:41], v[144:145]
	v_lshlrev_b32_e32 v39, 16, v77
	s_waitcnt vmcnt(37)
	v_lshlrev_b32_e32 v43, 16, v49
	v_lshlrev_b32_e32 v42, 16, v54
	ds_write_b16 v96, v35
	v_cvt_pk_bf16_f32 v35, v40, s0
	ds_write_b16 v96, v35 offset:17408
	v_mul_f32_e32 v35, v146, v39
	v_pk_mul_f32 v[144:145], v[146:147], v[42:43]
	v_mov_b32_e32 v146, v43
	v_pk_mul_f32 v[146:147], v[144:145], v[146:147]
	v_pk_add_f32 v[140:141], v[42:43], 1.0 op_sel_hi:[1,0] neg_lo:[1,0] neg_hi:[1,0]
	v_rcp_f32_e32 v42, v144
	v_rcp_f32_e32 v43, v146
	v_cvt_pk_bf16_f32 v35, v35, s0
	v_lshlrev_b32_e32 v117, 16, v79
	ds_write_b16 v96, v35 offset:272
	v_cvt_pk_bf16_f32 v35, v41, s0
	s_waitcnt vmcnt(31)
	v_lshlrev_b32_e32 v119, 16, v53
	v_lshlrev_b32_e32 v118, 16, v56
	ds_write_b16 v96, v35 offset:17680
	v_mul_f32_e32 v35, v144, v117
	v_cvt_pk_bf16_f32 v35, v35, s0
	v_pk_mul_f32 v[42:43], v[140:141], v[42:43]
	v_pk_mul_f32 v[140:141], v[146:147], v[118:119]
	v_mov_b32_e32 v144, v119
	v_lshlrev_b32_e32 v148, 16, v81
	ds_write_b16 v96, v35 offset:544
	v_cvt_pk_bf16_f32 v35, v42, s0
	v_pk_mul_f32 v[144:145], v[140:141], v[144:145]
	v_pk_add_f32 v[136:137], v[118:119], 1.0 op_sel_hi:[1,0] neg_lo:[1,0] neg_hi:[1,0]
	ds_write_b16 v96, v35 offset:17952
	v_mul_f32_e32 v35, v146, v148
	v_rcp_f32_e32 v118, v140
	v_rcp_f32_e32 v119, v144
	v_cvt_pk_bf16_f32 v35, v35, s0
	v_lshlrev_b32_e32 v149, 16, v83
	ds_write_b16 v96, v35 offset:816
	v_cvt_pk_bf16_f32 v35, v43, s0
	s_waitcnt vmcnt(25)
	v_lshlrev_b32_e32 v121, 16, v55
	v_lshlrev_b32_e32 v120, 16, v58
	ds_write_b16 v96, v35 offset:18224
	v_mul_f32_e32 v35, v140, v149
	v_cvt_pk_bf16_f32 v35, v35, s0
	v_pk_mul_f32 v[136:137], v[136:137], v[118:119]
	v_pk_mul_f32 v[118:119], v[144:145], v[120:121]
	v_mov_b32_e32 v140, v121
	v_lshlrev_b32_e32 v150, 16, v85
	ds_write_b16 v96, v35 offset:1088
	v_cvt_pk_bf16_f32 v35, v136, s0
	v_pk_mul_f32 v[140:141], v[118:119], v[140:141]
	v_pk_add_f32 v[132:133], v[120:121], 1.0 op_sel_hi:[1,0] neg_lo:[1,0] neg_hi:[1,0]
	ds_write_b16 v96, v35 offset:18496
	v_mul_f32_e32 v35, v144, v150
	v_rcp_f32_e32 v120, v118
	v_rcp_f32_e32 v121, v140
	v_cvt_pk_bf16_f32 v35, v35, s0
	v_lshlrev_b32_e32 v151, 16, v87
	ds_write_b16 v96, v35 offset:1360
	v_cvt_pk_bf16_f32 v35, v137, s0
	s_waitcnt vmcnt(19)
	v_lshlrev_b32_e32 v123, 16, v57
	v_lshlrev_b32_e32 v122, 16, v64
	ds_write_b16 v96, v35 offset:18768
	v_mul_f32_e32 v35, v118, v151
	v_pk_add_f32 v[142:143], v[122:123], 1.0 op_sel_hi:[1,0] neg_lo:[1,0] neg_hi:[1,0]
	v_cvt_pk_bf16_f32 v35, v35, s0
	v_pk_mul_f32 v[132:133], v[132:133], v[120:121]
	v_pk_mul_f32 v[118:119], v[140:141], v[122:123]
	v_mov_b32_e32 v122, v123
	v_lshlrev_b32_e32 v152, 16, v93
	ds_write_b16 v96, v35 offset:1632
	v_cvt_pk_bf16_f32 v35, v132, s0
	v_pk_mul_f32 v[122:123], v[118:119], v[122:123]
	ds_write_b16 v96, v35 offset:19040
	v_mul_f32_e32 v35, v140, v152
	v_rcp_f32_e32 v120, v118
	v_rcp_f32_e32 v121, v122
	v_cvt_pk_bf16_f32 v35, v35, s0
	v_lshlrev_b32_e32 v153, 16, v95
	ds_write_b16 v96, v35 offset:1904
	v_cvt_pk_bf16_f32 v35, v133, s0
	s_waitcnt vmcnt(13)
	v_lshlrev_b32_e32 v125, 16, v59
	v_lshlrev_b32_e32 v124, 16, v68
	ds_write_b16 v96, v35 offset:19312
	v_mul_f32_e32 v35, v118, v153
	v_pk_add_f32 v[138:139], v[124:125], 1.0 op_sel_hi:[1,0] neg_lo:[1,0] neg_hi:[1,0]
	v_cvt_pk_bf16_f32 v35, v35, s0
	v_pk_mul_f32 v[118:119], v[142:143], v[120:121]
	v_pk_mul_f32 v[120:121], v[122:123], v[124:125]
	v_mov_b32_e32 v124, v125
	v_lshlrev_b32_e32 v154, 16, v103
	ds_write_b16 v96, v35 offset:2176
	v_cvt_pk_bf16_f32 v35, v118, s0
	v_pk_mul_f32 v[124:125], v[120:121], v[124:125]
	ds_write_b16 v96, v35 offset:19584
	v_mul_f32_e32 v35, v122, v154
	v_rcp_f32_e32 v122, v120
	v_rcp_f32_e32 v123, v124
	v_cvt_pk_bf16_f32 v35, v35, s0
	v_lshlrev_b32_e32 v155, 16, v106
	ds_write_b16 v96, v35 offset:2448
	v_cvt_pk_bf16_f32 v35, v119, s0
	s_waitcnt vmcnt(7)
	v_lshlrev_b32_e32 v127, 16, v65
	v_lshlrev_b32_e32 v126, 16, v70
	ds_write_b16 v96, v35 offset:19856
	v_mul_f32_e32 v35, v120, v155
	v_pk_add_f32 v[134:135], v[126:127], 1.0 op_sel_hi:[1,0] neg_lo:[1,0] neg_hi:[1,0]
	v_cvt_pk_bf16_f32 v35, v35, s0
	v_pk_mul_f32 v[120:121], v[138:139], v[122:123]
	v_pk_mul_f32 v[122:123], v[124:125], v[126:127]
	v_mov_b32_e32 v126, v127
	v_lshlrev_b32_e32 v156, 16, v108
	ds_write_b16 v96, v35 offset:2720
	v_cvt_pk_bf16_f32 v35, v120, s0
	v_pk_mul_f32 v[126:127], v[122:123], v[126:127]
	ds_write_b16 v96, v35 offset:20128
	v_mul_f32_e32 v35, v124, v156
	v_rcp_f32_e32 v124, v122
	v_rcp_f32_e32 v125, v126
	v_cvt_pk_bf16_f32 v35, v35, s0
	v_lshlrev_b32_e32 v157, 16, v110
	ds_write_b16 v96, v35 offset:2992
	v_cvt_pk_bf16_f32 v35, v121, s0
	s_waitcnt vmcnt(0)
	v_lshlrev_b32_e32 v129, 16, v67
	v_lshlrev_b32_e32 v128, 16, v72
	ds_write_b16 v96, v35 offset:20400
	v_mul_f32_e32 v35, v122, v157
	v_pk_add_f32 v[130:131], v[128:129], 1.0 op_sel_hi:[1,0] neg_lo:[1,0] neg_hi:[1,0]
	v_cvt_pk_bf16_f32 v35, v35, s0
	v_pk_mul_f32 v[122:123], v[134:135], v[124:125]
	v_pk_mul_f32 v[124:125], v[126:127], v[128:129]
	v_mov_b32_e32 v128, v129
	v_lshlrev_b32_e32 v158, 16, v112
	ds_write_b16 v96, v35 offset:3264
	v_cvt_pk_bf16_f32 v35, v122, s0
	v_pk_mul_f32 v[128:129], v[124:125], v[128:129]
	ds_write_b16 v96, v35 offset:20672
	v_mul_f32_e32 v35, v126, v158
	v_rcp_f32_e32 v126, v124
	v_rcp_f32_e32 v127, v128
	v_cvt_pk_bf16_f32 v35, v35, s0
	v_lshlrev_b32_e32 v159, 16, v114
	ds_write_b16 v96, v35 offset:3536
	v_cvt_pk_bf16_f32 v35, v123, s0
	ds_write_b16 v96, v35 offset:20944
	v_mul_f32_e32 v35, v124, v159
	v_cvt_pk_bf16_f32 v35, v35, s0
	v_pk_mul_f32 v[124:125], v[130:131], v[126:127]
	v_lshlrev_b32_e32 v160, 16, v116
	ds_write_b16 v96, v35 offset:3808
	v_cvt_pk_bf16_f32 v35, v124, s0
	v_pk_mul_f32 v[40:41], v[40:41], v[128:129] op_sel_hi:[1,0]
	v_pk_mul_f32 v[42:43], v[42:43], v[128:129] op_sel_hi:[1,0]
	ds_write_b16 v96, v35 offset:21216
	v_mul_f32_e32 v35, v128, v160
	v_cvt_pk_bf16_f32 v40, v40, v41
	v_pk_mul_f32 v[118:119], v[118:119], v[128:129] op_sel_hi:[1,0]
	v_cvt_pk_bf16_f32 v41, v42, v43
	v_pk_mul_f32 v[42:43], v[120:121], v[128:129] op_sel_hi:[1,0]
	v_cvt_pk_bf16_f32 v35, v35, s0
	v_cvt_pk_bf16_f32 v118, v118, v119
	v_cvt_pk_bf16_f32 v119, v42, v43
	v_pk_mul_f32 v[42:43], v[136:137], v[128:129] op_sel_hi:[1,0]
	v_pk_mul_f32 v[120:121], v[128:129], v[122:123] op_sel_hi:[0,1]
	v_pk_mul_f32 v[122:123], v[132:133], v[128:129] op_sel_hi:[1,0]
	ds_write_b16 v96, v35 offset:4080
	v_cvt_pk_bf16_f32 v35, v125, s0
	v_cvt_pk_bf16_f32 v42, v42, v43
	v_cvt_pk_bf16_f32 v43, v122, v123
	v_pk_mul_f32 v[122:123], v[128:129], v[124:125] op_sel_hi:[0,1]
	v_lshl_or_b32 v32, v78, 16, v76
	v_lshl_or_b32 v36, v105, 16, v97
	v_lshl_or_b32 v33, v82, 16, v80
	v_lshl_or_b32 v37, v109, 16, v107
	v_lshl_or_b32 v34, v86, 16, v84
	v_lshl_or_b32 v38, v113, 16, v111
	ds_write_b16 v96, v35 offset:21488
	v_cvt_pk_bf16_f32 v120, v120, v121
	v_cvt_pk_bf16_f32 v121, v122, v123
	v_lshl_or_b32 v35, v94, 16, v89
	v_lshl_or_b32 v39, v51, 16, v115
	ds_write_b128 v91, v[40:43] offset:34816
	ds_write_b128 v91, v[118:121] offset:34832
	ds_write_b128 v91, v[32:35] offset:53248
	ds_write_b128 v91, v[36:39] offset:53264
	ds_write_b32 v92, v128
	s_cmp_eq_u32 s100, 0
	s_cbranch_scc0 .Lhp_afterprep
	s_mov_b32 s100, 1
	s_waitcnt lgkmcnt(0)
	v_add_u32_e32 v96, s99, v96
	v_add_u32_e32 v91, s99, v91
	v_add_u32_e32 v92, s99, v92
	s_add_i32 s48, s49, 1
	s_cmp_ge_u32 s48, s45
	s_cbranch_scc1 .Lhp_bar
	s_mov_b32 s101, 1
	s_branch .Lhp_issue
.Lhp_afterprep:
	s_add_i32 s48, s49, 2
	s_mov_b32 s101, 0
	s_cmp_ge_u32 s48, s45
	s_cbranch_scc1 .Lhp_postissue
.Lhp_issue:
	s_lshl_b32 s52, s48, 6
	s_sub_i32 s53, s46, s52
	s_and_b64 s[50:51], vcc, exec
	s_cselect_b32 s50, s52, s53
	v_add_u32_e32 v32, s50, v74
	v_mad_i64_i32 v[32:33], s[50:51], v32, s39, v[60:61]
	v_mov_b32_e32 v51, v45
	v_lshl_add_u64 v[34:35], v[32:33], 0, v[44:45]
	v_lshl_add_u64 v[38:39], v[32:33], 0, v[50:51]
	v_lshl_add_u64 v[32:33], s[34:35], 1, v[32:33]
	v_lshl_add_u64 v[40:41], v[32:33], 0, v[44:45]
	v_lshl_add_u64 v[54:55], v[32:33], 0, v[50:51]
	v_lshl_add_u64 v[32:33], v[32:33], 0, s[36:37]
	v_mov_b32_e32 v67, v45
	v_lshl_add_u64 v[56:57], v[32:33], 0, v[44:45]
	v_lshl_add_u64 v[36:37], v[34:35], 0, v[66:67]
	v_lshl_add_u64 v[42:43], v[40:41], 0, v[66:67]
	v_lshl_add_u64 v[58:59], v[56:57], 0, v[66:67]
	global_load_ushort v75, v[34:35], off
	global_load_ushort v52, v[36:37], off offset:2048
	global_load_ushort v76, v[38:39], off
	global_load_ushort v77, v[40:41], off
	global_load_ushort v47, v[42:43], off offset:2048
	global_load_ushort v78, v[54:55], off
	global_load_ushort v79, v[56:57], off
	s_nop 0
	global_load_ushort v54, v[58:59], off offset:2048
	v_lshl_add_u64 v[34:35], v[32:33], 0, v[50:51]
	v_lshl_add_u64 v[32:33], v[32:33], 0, s[36:37]
	v_lshl_add_u64 v[36:37], v[32:33], 0, v[44:45]
	v_lshl_add_u64 v[40:41], v[32:33], 0, v[50:51]
	v_lshl_add_u64 v[32:33], v[32:33], 0, s[36:37]
	v_lshl_add_u64 v[42:43], v[32:33], 0, v[44:45]
	v_lshl_add_u64 v[38:39], v[36:37], 0, v[66:67]
	global_load_ushort v80, v[34:35], off
	global_load_ushort v81, v[36:37], off
	global_load_ushort v49, v[38:39], off offset:2048
	global_load_ushort v82, v[40:41], off
	global_load_ushort v83, v[42:43], off
	v_lshl_add_u64 v[34:35], v[42:43], 0, v[66:67]
	global_load_ushort v56, v[34:35], off offset:2048
	v_lshl_add_u64 v[34:35], v[32:33], 0, v[50:51]
	v_lshl_add_u64 v[32:33], v[32:33], 0, s[36:37]
	v_lshl_add_u64 v[36:37], v[32:33], 0, v[44:45]
	global_load_ushort v84, v[34:35], off
	global_load_ushort v85, v[36:37], off
	v_lshl_add_u64 v[34:35], v[36:37], 0, v[66:67]
	global_load_ushort v53, v[34:35], off offset:2048
	v_lshl_add_u64 v[34:35], v[32:33], 0, v[50:51]
	v_lshl_add_u64 v[32:33], v[32:33], 0, s[36:37]
	global_load_ushort v86, v[34:35], off
	v_lshl_add_u64 v[34:35], v[32:33], 0, v[44:45]
	global_load_ushort v87, v[34:35], off
	v_lshl_add_u64 v[34:35], v[34:35], 0, v[66:67]
	global_load_ushort v58, v[34:35], off offset:2048
	v_lshl_add_u64 v[34:35], v[32:33], 0, v[50:51]
	v_lshl_add_u64 v[32:33], v[32:33], 0, s[36:37]
	global_load_ushort v89, v[34:35], off
	v_lshl_add_u64 v[34:35], v[32:33], 0, v[44:45]
	global_load_ushort v93, v[34:35], off
	v_lshl_add_u64 v[34:35], v[34:35], 0, v[66:67]
	global_load_ushort v55, v[34:35], off offset:2048
	v_lshl_add_u64 v[34:35], v[32:33], 0, v[50:51]
	v_lshl_add_u64 v[32:33], v[32:33], 0, s[36:37]
	global_load_ushort v94, v[34:35], off
	v_lshl_add_u64 v[34:35], v[32:33], 0, v[44:45]
	global_load_ushort v95, v[34:35], off
	v_lshl_add_u64 v[34:35], v[34:35], 0, v[66:67]
	global_load_ushort v64, v[34:35], off offset:2048
	v_lshl_add_u64 v[34:35], v[32:33], 0, v[50:51]
	v_lshl_add_u64 v[32:33], v[32:33], 0, s[36:37]
	global_load_ushort v97, v[34:35], off
	v_lshl_add_u64 v[34:35], v[32:33], 0, v[44:45]
	global_load_ushort v103, v[34:35], off
	v_lshl_add_u64 v[34:35], v[34:35], 0, v[66:67]
	global_load_ushort v57, v[34:35], off offset:2048
	v_lshl_add_u64 v[34:35], v[32:33], 0, v[50:51]
	v_lshl_add_u64 v[32:33], v[32:33], 0, s[36:37]
	global_load_ushort v105, v[34:35], off
	v_lshl_add_u64 v[34:35], v[32:33], 0, v[44:45]
	global_load_ushort v106, v[34:35], off
	v_lshl_add_u64 v[34:35], v[34:35], 0, v[66:67]
	global_load_ushort v68, v[34:35], off offset:2048
	v_lshl_add_u64 v[34:35], v[32:33], 0, v[50:51]
	v_lshl_add_u64 v[32:33], v[32:33], 0, s[36:37]
	global_load_ushort v107, v[34:35], off
	v_lshl_add_u64 v[34:35], v[32:33], 0, v[44:45]
	global_load_ushort v108, v[34:35], off
	v_lshl_add_u64 v[34:35], v[34:35], 0, v[66:67]
	global_load_ushort v59, v[34:35], off offset:2048
	v_lshl_add_u64 v[34:35], v[32:33], 0, v[50:51]
	v_lshl_add_u64 v[32:33], v[32:33], 0, s[36:37]
	global_load_ushort v109, v[34:35], off
	v_lshl_add_u64 v[34:35], v[32:33], 0, v[44:45]
	global_load_ushort v110, v[34:35], off
	v_lshl_add_u64 v[34:35], v[34:35], 0, v[66:67]
	global_load_ushort v70, v[34:35], off offset:2048
	v_lshl_add_u64 v[34:35], v[32:33], 0, v[50:51]
	v_lshl_add_u64 v[32:33], v[32:33], 0, s[36:37]
	global_load_ushort v111, v[34:35], off
	v_lshl_add_u64 v[34:35], v[32:33], 0, v[44:45]
	global_load_ushort v112, v[34:35], off
	v_lshl_add_u64 v[34:35], v[34:35], 0, v[66:67]
	global_load_ushort v65, v[34:35], off offset:2048
	v_lshl_add_u64 v[34:35], v[32:33], 0, v[50:51]
	v_lshl_add_u64 v[32:33], v[32:33], 0, s[36:37]
	global_load_ushort v113, v[34:35], off
	v_lshl_add_u64 v[34:35], v[32:33], 0, v[44:45]
	global_load_ushort v114, v[34:35], off
	v_lshl_add_u64 v[34:35], v[34:35], 0, v[66:67]
	global_load_ushort v72, v[34:35], off offset:2048
	v_lshl_add_u64 v[34:35], v[32:33], 0, v[50:51]
	v_lshl_add_u64 v[32:33], v[32:33], 0, s[36:37]
	global_load_ushort v115, v[34:35], off
	v_lshl_add_u64 v[34:35], v[32:33], 0, v[44:45]
	v_lshl_add_u64 v[32:33], v[32:33], 0, v[50:51]
	global_load_ushort v116, v[34:35], off
	global_load_ushort v51, v[32:33], off
	v_lshl_add_u64 v[34:35], v[34:35], 0, v[66:67]
	global_load_ushort v67, v[34:35], off offset:2048
	s_cmp_eq_u32 s101, 1
	s_cbranch_scc1 .Lhp_bar
.Lhp_postissue:
	s_cmp_eq_u32 s98, 0
	s_cbranch_scc1 .Lhp_end
.LBB0_1018:
	s_lshl_b32 s52, s49, 6
	s_sub_i32 s53, s46, s52
	s_and_b64 s[50:51], vcc, exec
	s_cselect_b32 s52, s52, s53
	v_add_u32_e32 v117, s52, v101
	v_add_u32_e32 v184, 0x11800, v98
	ds_read_b128 v[222:225], v104 offset:17408
	ds_read_b128 v[240:243], v104 offset:0
	ds_read_b128 v[228:231], v104 offset:17472
	ds_read_b128 v[244:247], v104 offset:64
	ds_read_b128 v[232:235], v104 offset:17536
	ds_read_b128 v[248:251], v104 offset:128
	ds_read_b128 v[236:239], v104 offset:17600
	ds_read_b128 v[252:255], v104 offset:192
	ds_read_b128 v[190:193], v104 offset:21760
	ds_read_b128 v[206:209], v104 offset:4352
	ds_read_b128 v[194:197], v104 offset:21824
	ds_read_b128 v[210:213], v104 offset:4416
	ds_read_b128 v[198:201], v104 offset:21888
	ds_read_b128 v[214:217], v104 offset:4480
	ds_read_b128 v[202:205], v104 offset:21952
	s_waitcnt lgkmcnt(7)
	v_mfma_f32_16x16x32_bf16 v[36:39], v[222:225], v[240:243], 0
	v_mfma_f32_16x16x32_bf16 v[36:39], v[228:231], v[244:247], v[36:39]
	v_mfma_f32_16x16x32_bf16 v[36:39], v[232:235], v[248:251], v[36:39]
	v_mfma_f32_16x16x32_bf16 v[36:39], v[236:239], v[252:255], v[36:39]
	ds_read_b128 v[218:221], v104 offset:4544
	ds_read_b128 v[222:225], v104 offset:26112
	ds_read_b128 v[240:243], v104 offset:8704
	ds_read_b128 v[228:231], v104 offset:26176
	ds_read_b128 v[244:247], v104 offset:8768
	ds_read_b128 v[232:235], v104 offset:26240
	ds_read_b128 v[248:251], v104 offset:8832
	ds_read_b128 v[236:239], v104 offset:26304
	s_waitcnt lgkmcnt(7)
	v_mfma_f32_16x16x32_bf16 v[40:43], v[190:193], v[206:209], 0
	v_mfma_f32_16x16x32_bf16 v[40:43], v[194:197], v[210:213], v[40:43]
	v_mfma_f32_16x16x32_bf16 v[40:43], v[198:201], v[214:217], v[40:43]
	v_mfma_f32_16x16x32_bf16 v[40:43], v[202:205], v[218:221], v[40:43]
	ds_read_b128 v[252:255], v104 offset:8896
	ds_read_b128 v[190:193], v104 offset:30464
	ds_read_b128 v[206:209], v104 offset:13056
	ds_read_b128 v[194:197], v104 offset:30528
	ds_read_b128 v[210:213], v104 offset:13120
	ds_read_b128 v[198:201], v104 offset:30592
	ds_read_b128 v[214:217], v104 offset:13184
	ds_read_b128 v[202:205], v104 offset:30656
	v_cndmask_b32_e64 v36, v36, 0, s[4:5]
	v_cndmask_b32_e64 v37, 0, v37, s[6:7]
	v_cndmask_b32_e64 v38, v38, 0, s[8:9]
	v_cndmask_b32_e64 v39, v39, 0, s[10:11]
	v_cvt_pk_bf16_f32 v176, v36, v37
	v_cvt_pk_bf16_f32 v177, v38, v39
	s_waitcnt lgkmcnt(7)
	v_mfma_f32_16x16x32_bf16 v[124:127], v[222:225], v[240:243], 0
	v_mfma_f32_16x16x32_bf16 v[124:127], v[228:231], v[244:247], v[124:127]
	v_mfma_f32_16x16x32_bf16 v[124:127], v[232:235], v[248:251], v[124:127]
	v_mfma_f32_16x16x32_bf16 v[124:127], v[236:239], v[252:255], v[124:127]
	ds_read_b128 v[218:221], v104 offset:13248
	v_cndmask_b32_e64 v40, v40, 0, s[4:5]
	v_cndmask_b32_e64 v41, 0, v41, s[6:7]
	v_cndmask_b32_e64 v42, v42, 0, s[8:9]
	v_cndmask_b32_e64 v43, v43, 0, s[10:11]
	v_cvt_pk_bf16_f32 v178, v40, v41
	v_cvt_pk_bf16_f32 v179, v42, v43
	s_waitcnt lgkmcnt(0)
	v_mfma_f32_16x16x32_bf16 v[128:131], v[190:193], v[206:209], 0
	v_mfma_f32_16x16x32_bf16 v[128:131], v[194:197], v[210:213], v[128:131]
	v_mfma_f32_16x16x32_bf16 v[128:131], v[198:201], v[214:217], v[128:131]
	v_mfma_f32_16x16x32_bf16 v[128:131], v[202:205], v[218:221], v[128:131]
	ds_read_b64 v[132:133], v102 offset:0
	ds_read_b64 v[134:135], v102 offset:32
	ds_read_b64 v[136:137], v102 offset:64
	ds_read_b64 v[138:139], v102 offset:96
	ds_read_b64 v[140:141], v102 offset:128
	ds_read_b64 v[142:143], v102 offset:160
	ds_read_b64 v[144:145], v102 offset:192
	ds_read_b64 v[146:147], v102 offset:224
	ds_read_b128 v[190:193], v184 offset:0
	ds_read_b128 v[194:197], v184 offset:64
	ds_read_b128 v[198:201], v184 offset:128
	ds_read_b128 v[202:205], v184 offset:192
	ds_read_b128 v[206:209], v184 offset:256
	ds_read_b128 v[210:213], v184 offset:320
	ds_read_b128 v[214:217], v184 offset:384
	v_cndmask_b32_e64 v124, v124, 0, s[4:5]
	v_cndmask_b32_e64 v125, 0, v125, s[6:7]
	v_cndmask_b32_e64 v126, v126, 0, s[8:9]
	v_cndmask_b32_e64 v127, v127, 0, s[10:11]
	v_cvt_pk_bf16_f32 v180, v124, v125
	v_cvt_pk_bf16_f32 v181, v126, v127
	v_mad_i64_i32 v[168:169], s[50:51], v117, s39, v[62:63]
	v_lshl_add_u64 v[170:171], s[34:35], 1, v[168:169]
	v_lshl_add_u64 v[172:173], v[170:171], 0, s[36:37]
	v_lshl_add_u64 v[174:175], v[172:173], 0, s[36:37]
	v_add_u32_e32 v117, s47, v117
	v_cndmask_b32_e64 v128, v128, 0, s[4:5]
	v_cndmask_b32_e64 v129, 0, v129, s[6:7]
	v_cndmask_b32_e64 v130, v130, 0, s[8:9]
	v_cndmask_b32_e64 v131, v131, 0, s[10:11]
	v_cvt_pk_bf16_f32 v182, v128, v129
	v_cvt_pk_bf16_f32 v183, v130, v131
	v_cvt_pk_bf16_f32 v36, v4, v5
	v_cvt_pk_bf16_f32 v37, v6, v7
	v_cvt_pk_bf16_f32 v38, v0, v1
	v_cvt_pk_bf16_f32 v39, v2, v3
	v_cvt_pk_bf16_f32 v40, v12, v13
	v_cvt_pk_bf16_f32 v41, v14, v15
	v_cvt_pk_bf16_f32 v42, v8, v9
	v_cvt_pk_bf16_f32 v43, v10, v11
	v_cvt_pk_bf16_f32 v124, v20, v21
	v_cvt_pk_bf16_f32 v125, v22, v23
	v_cvt_pk_bf16_f32 v126, v16, v17
	v_cvt_pk_bf16_f32 v127, v18, v19
	v_cvt_pk_bf16_f32 v128, v28, v29
	v_cvt_pk_bf16_f32 v129, v30, v31
	v_cvt_pk_bf16_f32 v130, v24, v25
	v_cvt_pk_bf16_f32 v131, v26, v27
	s_waitcnt lgkmcnt(7)
	s_nop 0
	v_mfma_f32_16x16x32_bf16 v[32:35], v[132:135], v[36:39], 0
	v_mfma_f32_16x16x32_bf16 v[32:35], v[136:139], v[40:43], v[32:35]
	v_mfma_f32_16x16x32_bf16 v[32:35], v[140:143], v[124:127], v[32:35]
	v_mfma_f32_16x16x32_bf16 v[32:35], v[144:147], v[128:131], v[32:35]
	ds_read_b128 v[218:221], v184 offset:448
	ds_read_b64 v[150:151], v100 offset:0
	ds_read_b64 v[152:153], v99 offset:0
	ds_read_b64 v[154:155], v99 offset:2304
	ds_read_b64 v[156:157], v99 offset:4608
	ds_read_b64 v[158:159], v99 offset:6912
	ds_read_b64 v[160:161], v99 offset:9216
	ds_read_b64 v[162:163], v99 offset:11520
	s_waitcnt lgkmcnt(7)
	v_pk_mul_f32 v[4:5], v[4:5], v[190:191]
	v_pk_mul_f32 v[6:7], v[6:7], v[192:193]
	v_pk_mul_f32 v[0:1], v[0:1], v[194:195]
	v_pk_mul_f32 v[2:3], v[2:3], v[196:197]
	v_pk_mul_f32 v[12:13], v[12:13], v[198:199]
	v_pk_mul_f32 v[14:15], v[14:15], v[200:201]
	v_pk_mul_f32 v[8:9], v[8:9], v[202:203]
	v_pk_mul_f32 v[10:11], v[10:11], v[204:205]
	v_pk_mul_f32 v[20:21], v[20:21], v[206:207]
	v_pk_mul_f32 v[22:23], v[22:23], v[208:209]
	v_pk_mul_f32 v[16:17], v[16:17], v[210:211]
	v_pk_mul_f32 v[18:19], v[18:19], v[212:213]
	v_pk_mul_f32 v[28:29], v[28:29], v[214:215]
	v_pk_mul_f32 v[30:31], v[30:31], v[216:217]
	v_pk_mul_f32 v[24:25], v[24:25], v[218:219]
	v_pk_mul_f32 v[26:27], v[26:27], v[220:221]
	ds_read_b64 v[164:165], v99 offset:13824
	ds_read_b64 v[166:167], v99 offset:16128
	s_waitcnt lgkmcnt(8)
	v_mfma_f32_16x16x16_bf16 v[32:35], v[176:177], v[150:151], v[32:35]
	s_waitcnt lgkmcnt(0)
	v_mfma_f32_16x16x16_bf16 v[4:7], v[152:153], v[150:151], v[4:7]
	v_mfma_f32_16x16x16_bf16 v[0:3], v[154:155], v[150:151], v[0:3]
	v_mfma_f32_16x16x16_bf16 v[12:15], v[156:157], v[150:151], v[12:15]
	v_mfma_f32_16x16x16_bf16 v[8:11], v[158:159], v[150:151], v[8:11]
	v_mfma_f32_16x16x16_bf16 v[20:23], v[160:161], v[150:151], v[20:23]
	v_mfma_f32_16x16x16_bf16 v[16:19], v[162:163], v[150:151], v[16:19]
	v_mfma_f32_16x16x16_bf16 v[28:31], v[164:165], v[150:151], v[28:31]
	v_mfma_f32_16x16x16_bf16 v[24:27], v[166:167], v[150:151], v[24:27]
	ds_read_b64 v[132:133], v102 offset:4352
	ds_read_b64 v[134:135], v102 offset:4384
	ds_read_b64 v[136:137], v102 offset:4416
	ds_read_b64 v[138:139], v102 offset:4448
	ds_read_b64 v[140:141], v102 offset:4480
	ds_read_b64 v[142:143], v102 offset:4512
	ds_read_b64 v[144:145], v102 offset:4544
	ds_read_b64 v[146:147], v102 offset:4576
	ds_read_b128 v[190:193], v184 offset:512
	ds_read_b128 v[194:197], v184 offset:576
	ds_read_b128 v[198:201], v184 offset:640
	ds_read_b128 v[202:205], v184 offset:704
	ds_read_b128 v[206:209], v184 offset:768
	ds_read_b128 v[210:213], v184 offset:832
	ds_read_b128 v[214:217], v184 offset:896
	v_cvt_pk_bf16_f32 v32, v32, s0
	v_cvt_pk_bf16_f32 v33, v33, s0
	v_cvt_pk_bf16_f32 v34, v34, s0
	v_cvt_pk_bf16_f32 v35, v35, s0
	global_store_short v[168:169], v32, off offset:2048
	global_store_short v[170:171], v33, off offset:2048
	global_store_short v[172:173], v34, off offset:2048
	global_store_short v[174:175], v35, off offset:2048
	v_mad_i64_i32 v[168:169], s[50:51], v117, s39, v[62:63]
	v_lshl_add_u64 v[170:171], s[34:35], 1, v[168:169]
	v_lshl_add_u64 v[172:173], v[170:171], 0, s[36:37]
	v_lshl_add_u64 v[174:175], v[172:173], 0, s[36:37]
	v_add_u32_e32 v117, s47, v117
	v_cvt_pk_bf16_f32 v36, v4, v5
	v_cvt_pk_bf16_f32 v37, v6, v7
	v_cvt_pk_bf16_f32 v38, v0, v1
	v_cvt_pk_bf16_f32 v39, v2, v3
	v_cvt_pk_bf16_f32 v40, v12, v13
	v_cvt_pk_bf16_f32 v41, v14, v15
	v_cvt_pk_bf16_f32 v42, v8, v9
	v_cvt_pk_bf16_f32 v43, v10, v11
	v_cvt_pk_bf16_f32 v124, v20, v21
	v_cvt_pk_bf16_f32 v125, v22, v23
	v_cvt_pk_bf16_f32 v126, v16, v17
	v_cvt_pk_bf16_f32 v127, v18, v19
	v_cvt_pk_bf16_f32 v128, v28, v29
	v_cvt_pk_bf16_f32 v129, v30, v31
	v_cvt_pk_bf16_f32 v130, v24, v25
	v_cvt_pk_bf16_f32 v131, v26, v27
	s_waitcnt lgkmcnt(7)
	s_nop 0
	v_mfma_f32_16x16x32_bf16 v[32:35], v[132:135], v[36:39], 0
	v_mfma_f32_16x16x32_bf16 v[32:35], v[136:139], v[40:43], v[32:35]
	v_mfma_f32_16x16x32_bf16 v[32:35], v[140:143], v[124:127], v[32:35]
	v_mfma_f32_16x16x32_bf16 v[32:35], v[144:147], v[128:131], v[32:35]
	ds_read_b128 v[218:221], v184 offset:960
	ds_read_b64 v[150:151], v100 offset:32
	ds_read_b64 v[152:153], v99 offset:32
	ds_read_b64 v[154:155], v99 offset:2336
	ds_read_b64 v[156:157], v99 offset:4640
	ds_read_b64 v[158:159], v99 offset:6944
	ds_read_b64 v[160:161], v99 offset:9248
	ds_read_b64 v[162:163], v99 offset:11552
	s_waitcnt lgkmcnt(7)
	v_pk_mul_f32 v[4:5], v[4:5], v[190:191]
	v_pk_mul_f32 v[6:7], v[6:7], v[192:193]
	v_pk_mul_f32 v[0:1], v[0:1], v[194:195]
	v_pk_mul_f32 v[2:3], v[2:3], v[196:197]
	v_pk_mul_f32 v[12:13], v[12:13], v[198:199]
	v_pk_mul_f32 v[14:15], v[14:15], v[200:201]
	v_pk_mul_f32 v[8:9], v[8:9], v[202:203]
	v_pk_mul_f32 v[10:11], v[10:11], v[204:205]
	v_pk_mul_f32 v[20:21], v[20:21], v[206:207]
	v_pk_mul_f32 v[22:23], v[22:23], v[208:209]
	v_pk_mul_f32 v[16:17], v[16:17], v[210:211]
	v_pk_mul_f32 v[18:19], v[18:19], v[212:213]
	v_pk_mul_f32 v[28:29], v[28:29], v[214:215]
	v_pk_mul_f32 v[30:31], v[30:31], v[216:217]
	v_pk_mul_f32 v[24:25], v[24:25], v[218:219]
	v_pk_mul_f32 v[26:27], v[26:27], v[220:221]
	ds_read_b64 v[164:165], v99 offset:13856
	ds_read_b64 v[166:167], v99 offset:16160
	s_waitcnt lgkmcnt(8)
	v_mfma_f32_16x16x16_bf16 v[32:35], v[178:179], v[150:151], v[32:35]
	s_waitcnt lgkmcnt(0)
	v_mfma_f32_16x16x16_bf16 v[4:7], v[152:153], v[150:151], v[4:7]
	v_mfma_f32_16x16x16_bf16 v[0:3], v[154:155], v[150:151], v[0:3]
	v_mfma_f32_16x16x16_bf16 v[12:15], v[156:157], v[150:151], v[12:15]
	v_mfma_f32_16x16x16_bf16 v[8:11], v[158:159], v[150:151], v[8:11]
	v_mfma_f32_16x16x16_bf16 v[20:23], v[160:161], v[150:151], v[20:23]
	v_mfma_f32_16x16x16_bf16 v[16:19], v[162:163], v[150:151], v[16:19]
	v_mfma_f32_16x16x16_bf16 v[28:31], v[164:165], v[150:151], v[28:31]
	v_mfma_f32_16x16x16_bf16 v[24:27], v[166:167], v[150:151], v[24:27]
	ds_read_b64 v[132:133], v102 offset:8704
	ds_read_b64 v[134:135], v102 offset:8736
	ds_read_b64 v[136:137], v102 offset:8768
	ds_read_b64 v[138:139], v102 offset:8800
	ds_read_b64 v[140:141], v102 offset:8832
	ds_read_b64 v[142:143], v102 offset:8864
	ds_read_b64 v[144:145], v102 offset:8896
	ds_read_b64 v[146:147], v102 offset:8928
	ds_read_b128 v[190:193], v184 offset:1024
	ds_read_b128 v[194:197], v184 offset:1088
	ds_read_b128 v[198:201], v184 offset:1152
	ds_read_b128 v[202:205], v184 offset:1216
	ds_read_b128 v[206:209], v184 offset:1280
	ds_read_b128 v[210:213], v184 offset:1344
	ds_read_b128 v[214:217], v184 offset:1408
	v_cvt_pk_bf16_f32 v32, v32, s0
	v_cvt_pk_bf16_f32 v33, v33, s0
	v_cvt_pk_bf16_f32 v34, v34, s0
	v_cvt_pk_bf16_f32 v35, v35, s0
	global_store_short v[168:169], v32, off offset:2048
	global_store_short v[170:171], v33, off offset:2048
	global_store_short v[172:173], v34, off offset:2048
	global_store_short v[174:175], v35, off offset:2048
	v_mad_i64_i32 v[168:169], s[50:51], v117, s39, v[62:63]
	v_lshl_add_u64 v[170:171], s[34:35], 1, v[168:169]
	v_lshl_add_u64 v[172:173], v[170:171], 0, s[36:37]
	v_lshl_add_u64 v[174:175], v[172:173], 0, s[36:37]
	v_add_u32_e32 v117, s47, v117
	v_cvt_pk_bf16_f32 v36, v4, v5
	v_cvt_pk_bf16_f32 v37, v6, v7
	v_cvt_pk_bf16_f32 v38, v0, v1
	v_cvt_pk_bf16_f32 v39, v2, v3
	v_cvt_pk_bf16_f32 v40, v12, v13
	v_cvt_pk_bf16_f32 v41, v14, v15
	v_cvt_pk_bf16_f32 v42, v8, v9
	v_cvt_pk_bf16_f32 v43, v10, v11
	v_cvt_pk_bf16_f32 v124, v20, v21
	v_cvt_pk_bf16_f32 v125, v22, v23
	v_cvt_pk_bf16_f32 v126, v16, v17
	v_cvt_pk_bf16_f32 v127, v18, v19
	v_cvt_pk_bf16_f32 v128, v28, v29
	v_cvt_pk_bf16_f32 v129, v30, v31
	v_cvt_pk_bf16_f32 v130, v24, v25
	v_cvt_pk_bf16_f32 v131, v26, v27
	s_waitcnt lgkmcnt(7)
	s_nop 0
	v_mfma_f32_16x16x32_bf16 v[32:35], v[132:135], v[36:39], 0
	v_mfma_f32_16x16x32_bf16 v[32:35], v[136:139], v[40:43], v[32:35]
	v_mfma_f32_16x16x32_bf16 v[32:35], v[140:143], v[124:127], v[32:35]
	v_mfma_f32_16x16x32_bf16 v[32:35], v[144:147], v[128:131], v[32:35]
	ds_read_b128 v[218:221], v184 offset:1472
	ds_read_b64 v[150:151], v100 offset:64
	ds_read_b64 v[152:153], v99 offset:64
	ds_read_b64 v[154:155], v99 offset:2368
	ds_read_b64 v[156:157], v99 offset:4672
	ds_read_b64 v[158:159], v99 offset:6976
	ds_read_b64 v[160:161], v99 offset:9280
	ds_read_b64 v[162:163], v99 offset:11584
	s_waitcnt lgkmcnt(7)
	v_pk_mul_f32 v[4:5], v[4:5], v[190:191]
	v_pk_mul_f32 v[6:7], v[6:7], v[192:193]
	v_pk_mul_f32 v[0:1], v[0:1], v[194:195]
	v_pk_mul_f32 v[2:3], v[2:3], v[196:197]
	v_pk_mul_f32 v[12:13], v[12:13], v[198:199]
	v_pk_mul_f32 v[14:15], v[14:15], v[200:201]
	v_pk_mul_f32 v[8:9], v[8:9], v[202:203]
	v_pk_mul_f32 v[10:11], v[10:11], v[204:205]
	v_pk_mul_f32 v[20:21], v[20:21], v[206:207]
	v_pk_mul_f32 v[22:23], v[22:23], v[208:209]
	v_pk_mul_f32 v[16:17], v[16:17], v[210:211]
	v_pk_mul_f32 v[18:19], v[18:19], v[212:213]
	v_pk_mul_f32 v[28:29], v[28:29], v[214:215]
	v_pk_mul_f32 v[30:31], v[30:31], v[216:217]
	v_pk_mul_f32 v[24:25], v[24:25], v[218:219]
	v_pk_mul_f32 v[26:27], v[26:27], v[220:221]
	ds_read_b64 v[164:165], v99 offset:13888
	ds_read_b64 v[166:167], v99 offset:16192
	s_waitcnt lgkmcnt(8)
	v_mfma_f32_16x16x16_bf16 v[32:35], v[180:181], v[150:151], v[32:35]
	s_waitcnt lgkmcnt(0)
	v_mfma_f32_16x16x16_bf16 v[4:7], v[152:153], v[150:151], v[4:7]
	v_mfma_f32_16x16x16_bf16 v[0:3], v[154:155], v[150:151], v[0:3]
	v_mfma_f32_16x16x16_bf16 v[12:15], v[156:157], v[150:151], v[12:15]
	v_mfma_f32_16x16x16_bf16 v[8:11], v[158:159], v[150:151], v[8:11]
	v_mfma_f32_16x16x16_bf16 v[20:23], v[160:161], v[150:151], v[20:23]
	v_mfma_f32_16x16x16_bf16 v[16:19], v[162:163], v[150:151], v[16:19]
	v_mfma_f32_16x16x16_bf16 v[28:31], v[164:165], v[150:151], v[28:31]
	v_mfma_f32_16x16x16_bf16 v[24:27], v[166:167], v[150:151], v[24:27]
	ds_read_b64 v[132:133], v102 offset:13056
	ds_read_b64 v[134:135], v102 offset:13088
	ds_read_b64 v[136:137], v102 offset:13120
	ds_read_b64 v[138:139], v102 offset:13152
	ds_read_b64 v[140:141], v102 offset:13184
	ds_read_b64 v[142:143], v102 offset:13216
	ds_read_b64 v[144:145], v102 offset:13248
	ds_read_b64 v[146:147], v102 offset:13280
	ds_read_b128 v[190:193], v184 offset:1536
	ds_read_b128 v[194:197], v184 offset:1600
	ds_read_b128 v[198:201], v184 offset:1664
	ds_read_b128 v[202:205], v184 offset:1728
	ds_read_b128 v[206:209], v184 offset:1792
	ds_read_b128 v[210:213], v184 offset:1856
	ds_read_b128 v[214:217], v184 offset:1920
	v_cvt_pk_bf16_f32 v32, v32, s0
	v_cvt_pk_bf16_f32 v33, v33, s0
	v_cvt_pk_bf16_f32 v34, v34, s0
	v_cvt_pk_bf16_f32 v35, v35, s0
	global_store_short v[168:169], v32, off offset:2048
	global_store_short v[170:171], v33, off offset:2048
	global_store_short v[172:173], v34, off offset:2048
	global_store_short v[174:175], v35, off offset:2048
	v_mad_i64_i32 v[168:169], s[50:51], v117, s39, v[62:63]
	v_lshl_add_u64 v[170:171], s[34:35], 1, v[168:169]
	v_lshl_add_u64 v[172:173], v[170:171], 0, s[36:37]
	v_lshl_add_u64 v[174:175], v[172:173], 0, s[36:37]
	v_add_u32_e32 v117, s47, v117
	v_cvt_pk_bf16_f32 v36, v4, v5
	v_cvt_pk_bf16_f32 v37, v6, v7
	v_cvt_pk_bf16_f32 v38, v0, v1
	v_cvt_pk_bf16_f32 v39, v2, v3
	v_cvt_pk_bf16_f32 v40, v12, v13
	v_cvt_pk_bf16_f32 v41, v14, v15
	v_cvt_pk_bf16_f32 v42, v8, v9
	v_cvt_pk_bf16_f32 v43, v10, v11
	v_cvt_pk_bf16_f32 v124, v20, v21
	v_cvt_pk_bf16_f32 v125, v22, v23
	v_cvt_pk_bf16_f32 v126, v16, v17
	v_cvt_pk_bf16_f32 v127, v18, v19
	v_cvt_pk_bf16_f32 v128, v28, v29
	v_cvt_pk_bf16_f32 v129, v30, v31
	v_cvt_pk_bf16_f32 v130, v24, v25
	v_cvt_pk_bf16_f32 v131, v26, v27
	s_waitcnt lgkmcnt(7)
	s_nop 0
	v_mfma_f32_16x16x32_bf16 v[32:35], v[132:135], v[36:39], 0
	v_mfma_f32_16x16x32_bf16 v[32:35], v[136:139], v[40:43], v[32:35]
	v_mfma_f32_16x16x32_bf16 v[32:35], v[140:143], v[124:127], v[32:35]
	v_mfma_f32_16x16x32_bf16 v[32:35], v[144:147], v[128:131], v[32:35]
	ds_read_b128 v[218:221], v184 offset:1984
	ds_read_b64 v[150:151], v100 offset:96
	ds_read_b64 v[152:153], v99 offset:96
	ds_read_b64 v[154:155], v99 offset:2400
	ds_read_b64 v[156:157], v99 offset:4704
	ds_read_b64 v[158:159], v99 offset:7008
	ds_read_b64 v[160:161], v99 offset:9312
	ds_read_b64 v[162:163], v99 offset:11616
	s_waitcnt lgkmcnt(7)
	v_pk_mul_f32 v[4:5], v[4:5], v[190:191]
	v_pk_mul_f32 v[6:7], v[6:7], v[192:193]
	v_pk_mul_f32 v[0:1], v[0:1], v[194:195]
	v_pk_mul_f32 v[2:3], v[2:3], v[196:197]
	v_pk_mul_f32 v[12:13], v[12:13], v[198:199]
	v_pk_mul_f32 v[14:15], v[14:15], v[200:201]
	v_pk_mul_f32 v[8:9], v[8:9], v[202:203]
	v_pk_mul_f32 v[10:11], v[10:11], v[204:205]
	v_pk_mul_f32 v[20:21], v[20:21], v[206:207]
	v_pk_mul_f32 v[22:23], v[22:23], v[208:209]
	v_pk_mul_f32 v[16:17], v[16:17], v[210:211]
	v_pk_mul_f32 v[18:19], v[18:19], v[212:213]
	v_pk_mul_f32 v[28:29], v[28:29], v[214:215]
	v_pk_mul_f32 v[30:31], v[30:31], v[216:217]
	v_pk_mul_f32 v[24:25], v[24:25], v[218:219]
	v_pk_mul_f32 v[26:27], v[26:27], v[220:221]
	ds_read_b64 v[164:165], v99 offset:13920
	ds_read_b64 v[166:167], v99 offset:16224
	s_waitcnt lgkmcnt(8)
	v_mfma_f32_16x16x16_bf16 v[32:35], v[182:183], v[150:151], v[32:35]
	s_waitcnt lgkmcnt(0)
	v_mfma_f32_16x16x16_bf16 v[4:7], v[152:153], v[150:151], v[4:7]
	v_mfma_f32_16x16x16_bf16 v[0:3], v[154:155], v[150:151], v[0:3]
	v_mfma_f32_16x16x16_bf16 v[12:15], v[156:157], v[150:151], v[12:15]
	v_mfma_f32_16x16x16_bf16 v[8:11], v[158:159], v[150:151], v[8:11]
	v_mfma_f32_16x16x16_bf16 v[20:23], v[160:161], v[150:151], v[20:23]
	v_mfma_f32_16x16x16_bf16 v[16:19], v[162:163], v[150:151], v[16:19]
	v_mfma_f32_16x16x16_bf16 v[28:31], v[164:165], v[150:151], v[28:31]
	v_mfma_f32_16x16x16_bf16 v[24:27], v[166:167], v[150:151], v[24:27]
	v_cvt_pk_bf16_f32 v32, v32, s0
	v_cvt_pk_bf16_f32 v33, v33, s0
	v_cvt_pk_bf16_f32 v34, v34, s0
	v_cvt_pk_bf16_f32 v35, v35, s0
	global_store_short v[168:169], v32, off offset:2048
	global_store_short v[170:171], v33, off offset:2048
	global_store_short v[172:173], v34, off offset:2048
	global_store_short v[174:175], v35, off offset:2048
	s_cmp_lg_u32 s98, 0
	s_cbranch_scc1 .Lhp_end
	s_add_i32 s48, s49, 1
	s_cmp_ge_u32 s48, s45
	s_cbranch_scc1 .Lhp_end
	s_branch .LBB0_1016

.Lhp_bar:
	s_waitcnt lgkmcnt(0)
	s_barrier
	s_cmp_eq_u32 s98, 0
	s_cbranch_scc1 .Lhp_ytop
	s_add_i32 s48, s49, 1
	s_cmp_ge_u32 s48, s45
	s_cbranch_scc1 .LBB0_1018
	s_branch .LBB0_1016
.Lhp_ytop:
	s_branch .LBB0_1018
.Lhp_exit:
	s_and_b64 vcc, exec, s[18:19]
	s_cbranch_vccz .LBB0_1007
	s_load_dwordx2 s[4:5], s[12:13], 0xa8
	s_waitcnt vmcnt(41)
	v_mov_b32_e32 v49, v45
	v_lshlrev_b64 v[34:35], 19, v[48:49]
	v_mov_b32_e32 v47, v45
	v_lshl_add_u32 v32, v73, 9, v71
	s_waitcnt lgkmcnt(0)
	v_lshl_add_u64 v[34:35], s[4:5], 0, v[34:35]
	v_lshl_add_u64 v[34:35], v[34:35], 0, v[46:47]
	v_lshl_add_u64 v[34:35], v[34:35], 0, s[16:17]
	v_ashrrev_i32_e32 v33, 31, v32
	v_lshl_add_u64 v[36:37], v[32:33], 2, v[34:35]
	global_store_dword v[36:37], v4, off
	global_store_dword v[36:37], v5, off offset:512
	v_lshl_add_u32 v4, v90, 7, v71
	v_ashrrev_i32_e32 v5, 31, v4
	v_lshl_add_u64 v[4:5], v[4:5], 2, v[34:35]
	global_store_dword v[4:5], v6, off
	v_lshl_add_u32 v4, v88, 7, v71
	v_ashrrev_i32_e32 v5, 31, v4
	v_lshl_add_u64 v[4:5], v[4:5], 2, v[34:35]
	global_store_dword v[4:5], v7, off
	v_add_u32_e32 v4, 0x800, v32
	v_ashrrev_i32_e32 v5, 31, v4
	v_lshl_add_u64 v[4:5], v[4:5], 2, v[34:35]
	global_store_dword v[4:5], v0, off
	v_add_u32_e32 v4, 0x880, v32
	v_ashrrev_i32_e32 v5, 31, v4
	v_lshl_add_u64 v[4:5], v[4:5], 2, v[34:35]
	v_add_u32_e32 v0, 0x900, v32
	global_store_dword v[4:5], v1, off
	v_ashrrev_i32_e32 v1, 31, v0
	v_lshl_add_u64 v[0:1], v[0:1], 2, v[34:35]
	global_store_dword v[0:1], v2, off
	v_add_u32_e32 v0, 0x980, v32
	v_ashrrev_i32_e32 v1, 31, v0
	v_lshl_add_u64 v[0:1], v[0:1], 2, v[34:35]
	global_store_dword v[0:1], v3, off
	v_add_u32_e32 v0, 0x1000, v32
	v_ashrrev_i32_e32 v1, 31, v0
	v_lshl_add_u64 v[0:1], v[0:1], 2, v[34:35]
	global_store_dword v[0:1], v12, off
	v_add_u32_e32 v0, 0x1080, v32
	v_ashrrev_i32_e32 v1, 31, v0
	v_lshl_add_u64 v[0:1], v[0:1], 2, v[34:35]
	global_store_dword v[0:1], v13, off
	v_add_u32_e32 v0, 0x1100, v32
	v_ashrrev_i32_e32 v1, 31, v0
	v_lshl_add_u64 v[0:1], v[0:1], 2, v[34:35]
	global_store_dword v[0:1], v14, off
	v_add_u32_e32 v0, 0x1180, v32
	v_ashrrev_i32_e32 v1, 31, v0
	v_lshl_add_u64 v[0:1], v[0:1], 2, v[34:35]
	global_store_dword v[0:1], v15, off
	v_add_u32_e32 v0, 0x1800, v32
	v_ashrrev_i32_e32 v1, 31, v0
	v_lshl_add_u64 v[0:1], v[0:1], 2, v[34:35]
	global_store_dword v[0:1], v8, off
	v_add_u32_e32 v0, 0x1880, v32
	v_ashrrev_i32_e32 v1, 31, v0
	v_lshl_add_u64 v[0:1], v[0:1], 2, v[34:35]
	global_store_dword v[0:1], v9, off
	v_add_u32_e32 v0, 0x1900, v32
	v_ashrrev_i32_e32 v1, 31, v0
	v_lshl_add_u64 v[0:1], v[0:1], 2, v[34:35]
	global_store_dword v[0:1], v10, off
	v_add_u32_e32 v0, 0x1980, v32
	v_ashrrev_i32_e32 v1, 31, v0
	v_lshl_add_u64 v[0:1], v[0:1], 2, v[34:35]
	global_store_dword v[0:1], v11, off
	v_add_u32_e32 v0, 0x2000, v32
	v_ashrrev_i32_e32 v1, 31, v0
	v_lshl_add_u64 v[0:1], v[0:1], 2, v[34:35]
	global_store_dword v[0:1], v20, off
	v_add_u32_e32 v0, 0x2080, v32
	v_ashrrev_i32_e32 v1, 31, v0
	v_lshl_add_u64 v[0:1], v[0:1], 2, v[34:35]
	global_store_dword v[0:1], v21, off
	v_add_u32_e32 v0, 0x2100, v32
	v_ashrrev_i32_e32 v1, 31, v0
	v_lshl_add_u64 v[0:1], v[0:1], 2, v[34:35]
	global_store_dword v[0:1], v22, off
	v_add_u32_e32 v0, 0x2180, v32
	v_ashrrev_i32_e32 v1, 31, v0
	v_lshl_add_u64 v[0:1], v[0:1], 2, v[34:35]
	global_store_dword v[0:1], v23, off
	v_add_u32_e32 v0, 0x2800, v32
	v_ashrrev_i32_e32 v1, 31, v0
	v_lshl_add_u64 v[0:1], v[0:1], 2, v[34:35]
	global_store_dword v[0:1], v16, off
	v_add_u32_e32 v0, 0x2880, v32
	v_ashrrev_i32_e32 v1, 31, v0
	v_lshl_add_u64 v[0:1], v[0:1], 2, v[34:35]
	global_store_dword v[0:1], v17, off
	v_add_u32_e32 v0, 0x2900, v32
	v_ashrrev_i32_e32 v1, 31, v0
	v_lshl_add_u64 v[0:1], v[0:1], 2, v[34:35]
	global_store_dword v[0:1], v18, off
	v_add_u32_e32 v0, 0x2980, v32
	v_ashrrev_i32_e32 v1, 31, v0
	v_lshl_add_u64 v[0:1], v[0:1], 2, v[34:35]
	global_store_dword v[0:1], v19, off
	v_add_u32_e32 v0, 0x3000, v32
	v_ashrrev_i32_e32 v1, 31, v0
	v_lshl_add_u64 v[0:1], v[0:1], 2, v[34:35]
	global_store_dword v[0:1], v28, off
	v_add_u32_e32 v0, 0x3080, v32
	v_ashrrev_i32_e32 v1, 31, v0
	v_lshl_add_u64 v[0:1], v[0:1], 2, v[34:35]
	global_store_dword v[0:1], v29, off
	v_add_u32_e32 v0, 0x3100, v32
	v_ashrrev_i32_e32 v1, 31, v0
	v_lshl_add_u64 v[0:1], v[0:1], 2, v[34:35]
	global_store_dword v[0:1], v30, off
	v_add_u32_e32 v0, 0x3180, v32
	v_ashrrev_i32_e32 v1, 31, v0
	v_lshl_add_u64 v[0:1], v[0:1], 2, v[34:35]
	global_store_dword v[0:1], v31, off
	v_add_u32_e32 v0, 0x3800, v32
	v_ashrrev_i32_e32 v1, 31, v0
	v_lshl_add_u64 v[0:1], v[0:1], 2, v[34:35]
	global_store_dword v[0:1], v24, off
	v_add_u32_e32 v0, 0x3880, v32
	v_ashrrev_i32_e32 v1, 31, v0
	v_lshl_add_u64 v[0:1], v[0:1], 2, v[34:35]
	global_store_dword v[0:1], v25, off
	v_add_u32_e32 v0, 0x3900, v32
	v_ashrrev_i32_e32 v1, 31, v0
	v_lshl_add_u64 v[0:1], v[0:1], 2, v[34:35]
	global_store_dword v[0:1], v26, off
	v_add_u32_e32 v0, 0x3980, v32
	v_ashrrev_i32_e32 v1, 31, v0
	v_lshl_add_u64 v[0:1], v[0:1], 2, v[34:35]
	global_store_dword v[0:1], v27, off
	s_branch .LBB0_1007
